# non-scan WGs wait ~32us after the group-prefix pass before starting the late operand tiles (less memory contention while the scan fills its ring)
# baseline (speedup 1.0000x reference)
; #define LAS __attribute__((address_space(3)))
; __device__ __forceinline__ v2u pk4(f32x4 v) { v2u o; o.x = pk2(v.x, v.y); o.y = pk2(v.z, v.w); return o; }
; __device__ __forceinline__ float fast_tanh(float x) { x = fminf(fmaxf(x, -15.f), 15.f); const float e = __expf(2.f * x); return (e - 1.f) / (e + 1.f); }
; __device__ __forceinline__ void p2_rwprep_tile(Frame& F, const Args& a, int t0) {
;     unsigned char* ws = a.ws;
;     const float* ZS = (const float*)(ws + WS_ZS);
;     LAS bf16* TD = (LAS bf16*)F.lds; LAS bf16* DA = TD + 32 * 64;
;     {
;         const int tok = F.tid >> 4, c4 = (F.tid & 15) * 4, t = t0 + tok;
;         const f32x4 zero = {0.f, 0.f, 0.f, 0.f};
;         const f32x4 cw = ld4(ZS + (size_t)t * 256 + c4), ca = ld4(ZS + (size_t)t * 256 + 64 + c4);
;         const f32x4 pw = t > 0 ? ld4(ZS + (size_t)(t - 1) * 256 + c4) : zero, pa = t > 0 ? ld4(ZS + (size_t)(t - 1) * 256 + 64 + c4) : zero;
;         const f32x4 mw = ld4(a.in[7] + c4), ma = ld4(a.in[8] + c4);
;         f32x4 dw = cw + (pw - cw) * mw, da = ca + (pa - ca) * ma;
;         dw.x = fast_tanh(dw.x); dw.y = fast_tanh(dw.y); dw.z = fast_tanh(dw.z); dw.w = fast_tanh(dw.w);
;         *(LAS v2u*)(TD + tok * 64 + c4) = pk4(dw); *(LAS v2u*)(DA + tok * 64 + c4) = pk4(da);
;     }
;     __syncthreads();
;     LAS unsigned char* lw_ = F.lds + 8192 + F.wave * 10240;
;     for (int q = 0; q < 4; ++q) { const int hh = q >> 1, rb = q & 1; rw_chunk_prep(a, 2 * F.wave + hh, t0 + rb * 16, TD + rb * 16 * 64, DA + rb * 16 * 64, lw_, F.lane); }
;     __syncthreads();
; }
; __global__ void __launch_bounds__(NTHR, 2) hybrid_fwd(Args args) {
;     ...
;         for (int tile = blockIdx.x; tile < T / 32; tile += F.G) p2_rwprep_tile(F, args, tile * 32); }
.Lfg_pub_skip:
	s_movk_i32 s99, 10
.Lp3_stagger:
	s_sleep 127
	s_sub_u32 s99, s99, 1
	s_cmp_lg_u32 s99, 0
	s_cbranch_scc1 .Lp3_stagger
	s_mov_b32 s98, 1
	v_readlane_b32 s36, v255, 8
	v_readlane_b32 s37, v255, 9
	v_readlane_b32 s38, v255, 10
	v_readlane_b32 s39, v255, 11
	v_readlane_b32 s40, v255, 12
	v_readlane_b32 s41, v255, 13
	v_readlane_b32 s42, v255, 14
	v_readlane_b32 s43, v255, 15
	v_readlane_b32 s44, v255, 16
	v_readlane_b32 s45, v255, 17
	v_readlane_b32 s46, v255, 18
	v_readlane_b32 s47, v255, 19
	v_readlane_b32 s48, v255, 20
	v_readlane_b32 s49, v255, 21
	v_readlane_b32 s50, v255, 22
	v_readlane_b32 s51, v255, 23
	s_add_u32 s6, s90, 0x3300000
	s_addc_u32 s7, s91, 0
	s_add_u32 s8, s90, 0x3380000
	s_addc_u32 s9, s91, 0
	s_add_u32 s14, s90, 0x8000000
	s_addc_u32 s15, s91, 0
	v_mbcnt_lo_u32_b32 v10, -1, 0
	v_mbcnt_hi_u32_b32 v10, -1, v10
	v_and_b32_e32 v11, 15, v10
	v_lshlrev_b32_e32 v0, 4, v10
	s_nop 4
	s_branch .Lrw_again
